# v16 with CVX 3200->1152 (sample team converts fewer layer-1 w_in items beside the scan jobs; branch tail 7 rounds)
# speedup vs baseline: 1.0005x; 1.0005x over previous
.LBB0_80:
	v_readlane_b32 s22, v248, 1
	v_readlane_b32 s23, v248, 2
	s_add_u32 s0, s22, 0x72d00000
	s_addc_u32 s1, s23, 0
	v_writelane_b32 v249, s0, 4
	v_readlane_b32 s24, v248, 7
	v_readlane_b32 s48, v248, 26
	v_writelane_b32 v249, s1, 5
	s_ashr_i32 s0, s24, 31
	v_readlane_b32 s50, v248, 28
	v_writelane_b32 v249, s0, 6
	v_readlane_b32 s51, v248, 29
	s_add_u32 s0, s50, 0x2000
	s_addc_u32 s1, s51, 0
	v_writelane_b32 v249, s0, 7
	s_cmpk_lg_i32 s24, 0x100
	v_readlane_b32 s13, v248, 43
	v_writelane_b32 v249, s1, 8
	s_cselect_b64 s[0:1], -1, 0
	v_writelane_b32 v249, s0, 9
	s_cmpk_lt_i32 s13, 0x1400
	v_readlane_b32 s21, v248, 0
	v_writelane_b32 v249, s1, 10
	s_cselect_b64 s[0:1], -1, 0
	v_writelane_b32 v249, s0, 11
	v_readlane_b32 s49, v248, 27
	v_mov_b32_e32 v34, 0
	v_writelane_b32 v249, s1, 12
	s_add_i32 s0, s13, 0x3c80
	s_add_u32 s9, s22, 0x24500000
	s_addc_u32 s12, s23, 0
	s_add_u32 s5, s22, 0x1e500000
	v_writelane_b32 v249, s0, 13
	s_addc_u32 s11, s23, 0
	s_add_i32 s0, s21, 0xffffff97
	s_cmpk_lt_u32 s0, 0x67
	s_cselect_b64 s[0:1], -1, 0
	v_writelane_b32 v249, s0, 14
	v_mov_b32_e32 v219, 1
	v_mov_b32_e32 v222, 0x358637bd
	v_writelane_b32 v249, s1, 15
	s_add_i32 s0, s13, 0xfffffcb8
	s_cmpk_lt_i32 s0, 0x1400
	s_cselect_b64 s[0:1], -1, 0
	v_writelane_b32 v249, s0, 16
	v_mov_b32_e32 v223, 0x260
	v_mov_b32_e32 v224, 0x3ecc95a3
	v_writelane_b32 v249, s1, 17
	s_add_i32 s0, s13, 0x3938
	v_writelane_b32 v249, s0, 18
	s_add_u32 s0, s22, 0x4200
	s_addc_u32 s1, s23, 0
	v_writelane_b32 v249, s0, 19
	v_mov_b32_e32 v225, 0x3e2aaaab
	v_mov_b64_e32 v[164:165], 0x969
	v_writelane_b32 v249, s1, 20
	s_add_u32 s0, s22, 0x4400
	s_addc_u32 s1, s23, 0
	v_writelane_b32 v249, s0, 21
	v_mov_b64_e32 v[166:167], 0x968
	v_mov_b32_e32 v226, 0x41b17218
	v_writelane_b32 v249, s1, 22
	s_add_u32 s0, s22, 0x4500
	s_addc_u32 s1, s23, 0
	v_writelane_b32 v249, s0, 23
	v_mov_b64_e32 v[168:169], 0x630
	v_mov_b64_e32 v[170:171], 0x62f
	v_writelane_b32 v249, s1, 24
	s_add_u32 s0, s22, 0x4600
	s_addc_u32 s1, s23, 0
	v_writelane_b32 v249, s0, 25
	v_mov_b32_e32 v227, 0x1e040
	v_mov_b32_e32 v228, 2
	v_writelane_b32 v249, s1, 26
	s_add_u32 s0, s22, 0x4700
	s_addc_u32 s1, s23, 0
	v_writelane_b32 v249, s0, 27
	v_mov_b32_e32 v230, 0x3000
	v_mov_b32_e32 v231, 0x7f800000
	v_writelane_b32 v249, s1, 28
	s_add_u32 s0, s22, 0x4800
	s_addc_u32 s1, s23, 0
	v_writelane_b32 v249, s0, 29
	v_readlane_b32 s52, v248, 30
	v_readlane_b32 s53, v248, 31
	v_writelane_b32 v249, s1, 30
	s_add_u32 s0, s22, 0x4900
	s_addc_u32 s1, s23, 0
	v_writelane_b32 v249, s0, 31
	v_readlane_b32 s54, v248, 32
	v_readlane_b32 s55, v248, 33
	v_writelane_b32 v249, s1, 32
	s_add_u32 s0, s22, 0x4a00
	s_addc_u32 s1, s23, 0
	v_writelane_b32 v249, s0, 33
	v_readlane_b32 s56, v248, 34
	v_readlane_b32 s57, v248, 35
	v_writelane_b32 v249, s1, 34
	s_add_u32 s0, s22, 0x4b00
	s_addc_u32 s1, s23, 0
	v_writelane_b32 v249, s0, 35
	v_readlane_b32 s58, v248, 36
	v_readlane_b32 s59, v248, 37
	v_writelane_b32 v249, s1, 36
	s_add_u32 s0, s22, 0x4c00
	s_addc_u32 s1, s23, 0
	v_writelane_b32 v249, s0, 37
	v_readlane_b32 s60, v248, 38
	v_readlane_b32 s61, v248, 39
	v_writelane_b32 v249, s1, 38
	s_add_u32 s0, s22, 0x4d00
	s_addc_u32 s1, s23, 0
	v_writelane_b32 v249, s0, 39
	v_readlane_b32 s62, v248, 40
	v_readlane_b32 s63, v248, 41
	v_writelane_b32 v249, s1, 40
	s_add_u32 s0, s22, 0x4e00
	s_addc_u32 s1, s23, 0
	v_writelane_b32 v249, s0, 41
	s_nop 1
	v_writelane_b32 v249, s1, 42
	s_add_u32 s0, s22, 0x4f00
	s_addc_u32 s1, s23, 0
	v_writelane_b32 v249, s0, 43
	s_nop 1
	v_writelane_b32 v249, s1, 44
	s_add_u32 s0, s22, 0x5000
	s_addc_u32 s1, s23, 0
	v_writelane_b32 v249, s0, 45
	s_nop 1
	v_writelane_b32 v249, s1, 46
	s_add_u32 s0, s22, 0x5100
	s_addc_u32 s1, s23, 0
	v_writelane_b32 v249, s0, 47
	s_nop 1
	v_writelane_b32 v249, s1, 48
	s_add_u32 s0, s22, 0x5200
	s_addc_u32 s1, s23, 0
	v_writelane_b32 v249, s0, 49
	s_nop 1
	v_writelane_b32 v249, s1, 50
	s_add_u32 s0, s22, 0x5300
	s_addc_u32 s1, s23, 0
	v_writelane_b32 v249, s0, 51
	s_cmp_eq_u32 s46, 15
	s_nop 0
	v_writelane_b32 v249, s1, 52
	s_cselect_b64 s[0:1], -1, 0
	v_writelane_b32 v249, s0, 53
	s_cmp_eq_u32 s46, 14
	s_nop 0
	v_writelane_b32 v249, s1, 54
	s_cselect_b64 s[0:1], -1, 0
	v_writelane_b32 v249, s0, 55
	s_cmp_eq_u32 s46, 13
	s_nop 0
	v_writelane_b32 v249, s1, 56
	s_cselect_b64 s[0:1], -1, 0
	v_writelane_b32 v249, s0, 57
	s_cmp_eq_u32 s46, 12
	s_nop 0
	v_writelane_b32 v249, s1, 58
	s_cselect_b64 s[0:1], -1, 0
	v_writelane_b32 v249, s0, 59
	s_cmp_eq_u32 s46, 11
	s_nop 0
	v_writelane_b32 v249, s1, 60
	s_cselect_b64 s[0:1], -1, 0
	v_writelane_b32 v249, s0, 61
	s_cmp_eq_u32 s46, 10
	s_nop 0
	v_writelane_b32 v249, s1, 62
	s_cselect_b64 s[0:1], -1, 0
	v_writelane_b32 v249, s0, 63
	s_cmp_eq_u32 s46, 9
	s_nop 0
	v_writelane_b32 v250, s1, 0
	s_cselect_b64 s[0:1], -1, 0
	v_writelane_b32 v250, s0, 1
	s_cmp_eq_u32 s46, 8
	s_nop 0
	v_writelane_b32 v250, s1, 2
	s_cselect_b64 s[0:1], -1, 0
	v_writelane_b32 v250, s0, 3
	s_cmp_eq_u32 s46, 7
	s_nop 0
	v_writelane_b32 v250, s1, 4
	s_cselect_b64 s[0:1], -1, 0
	v_writelane_b32 v250, s0, 5
	s_cmp_eq_u32 s46, 6
	s_nop 0
	v_writelane_b32 v250, s1, 6
	s_cselect_b64 s[0:1], -1, 0
	v_writelane_b32 v250, s0, 7
	s_cmp_eq_u32 s46, 5
	s_nop 0
	v_writelane_b32 v250, s1, 8
	s_cselect_b64 s[0:1], -1, 0
	v_writelane_b32 v250, s0, 9
	s_cmp_eq_u32 s46, 4
	s_nop 0
	v_writelane_b32 v250, s1, 10
	s_cselect_b64 s[0:1], -1, 0
	v_writelane_b32 v250, s0, 11
	s_cmp_eq_u32 s46, 3
	s_nop 0
	v_writelane_b32 v250, s1, 12
	s_cselect_b64 s[0:1], -1, 0
	v_writelane_b32 v250, s0, 13
	s_cmp_eq_u32 s46, 2
	s_nop 0
	v_writelane_b32 v250, s1, 14
	s_cselect_b64 s[0:1], -1, 0
	v_writelane_b32 v250, s0, 15
	s_cmp_eq_u32 s46, 1
	s_nop 0
	v_writelane_b32 v250, s1, 16
	s_cselect_b64 s[0:1], -1, 0
	v_writelane_b32 v250, s0, 17
	s_cmp_eq_u32 s46, 0
	s_nop 0
	v_writelane_b32 v250, s1, 18
	s_cselect_b64 s[0:1], -1, 0
	v_writelane_b32 v250, s0, 19
	s_nop 1
	v_writelane_b32 v250, s1, 20
	s_lshl_b32 s0, s46, 8
	s_add_u32 s0, s2, s0
	s_addc_u32 s1, s3, 0
	s_add_u32 s2, s0, 0x1400
	s_addc_u32 s3, s1, 0
	v_writelane_b32 v250, s2, 21
	s_add_u32 s0, s0, 0x2400
	s_addc_u32 s1, s1, 0
	v_writelane_b32 v250, s3, 22
	v_writelane_b32 v250, s0, 23
	s_nop 1
	v_writelane_b32 v250, s1, 24
	s_add_u32 s0, s22, 0x7400
	s_addc_u32 s1, s23, 0
	v_writelane_b32 v250, s0, 25
	s_nop 1
	v_writelane_b32 v250, s1, 26
	s_add_u32 s0, s22, 0x7500
	s_addc_u32 s1, s23, 0
	v_writelane_b32 v250, s0, 27
	s_cmpk_lt_i32 s21, 0x220
	s_nop 0
	v_writelane_b32 v250, s1, 28
	s_cselect_b64 s[0:1], -1, 0
	v_writelane_b32 v250, s0, 29
	s_ashr_i32 s14, s21, 31
	s_add_i32 s8, s21, 0xffffff40
	v_writelane_b32 v250, s1, 30
	s_lshr_b32 s0, s14, 26
	s_add_i32 s0, s21, s0
	s_ashr_i32 s7, s0, 6
	s_add_i32 s0, s24, 0xffffff40
	v_writelane_b32 v250, s0, 31
	s_sub_i32 s0, s21, 64
	s_cmpk_lt_i32 s21, 0x80
	s_cselect_b32 s25, s21, s0
	s_cmpk_lt_i32 s25, 0x220
	v_writelane_b32 v250, s0, 32
	s_cselect_b64 s[0:1], -1, 0
	v_writelane_b32 v250, s0, 33
	s_nop 1
	v_writelane_b32 v250, s1, 34
	s_add_u32 s0, s22, 0x12000
	v_writelane_b32 v250, s0, 35
	s_addc_u32 s0, s23, 0
	v_writelane_b32 v250, s0, 36
	s_add_i32 s0, s21, 0xffffff80
	v_writelane_b32 v250, s0, 37
	s_add_i32 s0, s21, 1
	v_writelane_b32 v250, s0, 38
	s_sub_i32 s0, s21, 63
	v_writelane_b32 v250, s0, 39
	s_add_i32 s0, s21, 0xffffff81
	s_cmpk_gt_i32 s21, 0xbf
	v_writelane_b32 v250, s0, 40
	s_cselect_b64 s[0:1], -1, 0
	s_cmpk_eq_i32 s24, 0x100
	s_cselect_b64 s[26:27], -1, 0
	s_and_b64 s[2:3], s[26:27], exec
	s_movk_i32 s2, 0x200
	s_cselect_b32 s6, s2, 0x210
	s_movk_i32 s2, 0x2000
	s_cselect_b32 s2, s2, 0x2100
	v_writelane_b32 v250, s2, 41
	s_cselect_b32 s19, 32, 33
	s_cselect_b32 s10, 0x480, 0
	s_and_b64 s[0:1], s[0:1], s[26:27]
	v_writelane_b32 v250, s0, 42
	s_nop 1
	v_writelane_b32 v250, s1, 43
	s_add_u32 s0, s22, 0x10000
	v_writelane_b32 v250, s0, 44
	s_addc_u32 s0, s23, 0
	v_writelane_b32 v250, s0, 45
	s_lshl_b32 s0, s8, 3
	s_add_i32 s15, s33, s0
	s_cmpk_lt_i32 s21, 0xf0
	s_mul_hi_i32 s0, s8, 0x55555556
	s_cselect_b64 s[2:3], -1, 0
	s_lshr_b32 s1, s0, 31
	s_add_i32 s1, s0, s1
	s_mul_i32 s0, s1, -3
	v_writelane_b32 v250, s2, 46
	s_add_i32 s0, s0, s8
	s_mul_i32 s4, s1, 0x300000
	v_writelane_b32 v250, s3, 47
	s_lshl_b32 s2, s0, 11
	s_ashr_i32 s3, s2, 31
	s_lshl_b64 s[28:29], s[2:3], 1
	s_add_u32 s2, s5, s28
	v_writelane_b32 v250, s5, 48
	s_addc_u32 s3, s11, s29
	v_writelane_b32 v250, s11, 49
	s_add_u32 s2, s2, s4
	s_mul_hi_i32 s5, s1, 0x300000
	v_writelane_b32 v250, s2, 50
	s_addc_u32 s2, s3, s5
	v_writelane_b32 v250, s2, 51
	s_lshl_b32 s1, s1, 8
	v_writelane_b32 v250, s1, 52
	s_ashr_i32 s1, s0, 31
	s_lshl_b64 s[2:3], s[0:1], 12
	v_writelane_b32 v250, s2, 53
	s_lshl_b64 s[0:1], s[0:1], 22
	s_ashr_i32 s8, s8, 2
	v_writelane_b32 v250, s3, 54
	v_writelane_b32 v250, s0, 55
	s_nop 1
	v_writelane_b32 v250, s1, 56
	s_and_b32 s0, s21, 3
	s_lshl_b32 s2, s0, 10
	s_lshl_b32 s30, s0, 11
	v_writelane_b32 v250, s9, 57
	s_add_u32 s11, s9, s30
	v_writelane_b32 v250, s12, 58
	s_addc_u32 s12, s12, 0
	s_ashr_i32 s9, s8, 31
	s_lshl_b32 s3, s0, 20
	s_lshl_b64 s[0:1], s[8:9], 21
	s_add_u32 s9, s11, s0
	v_writelane_b32 v250, s9, 59
	s_addc_u32 s9, s12, s1
	v_writelane_b32 v250, s9, 60
	s_lshl_b32 s8, s8, 8
	v_writelane_b32 v250, s8, 61
	s_cmpk_lt_i32 s15, 0x480
	v_writelane_b32 v250, s15, 62
	s_cselect_b64 s[8:9], -1, 0
	v_writelane_b32 v250, s8, 63
	s_nop 1
	v_writelane_b32 v251, s9, 0
	s_add_u32 s8, s48, 0x1e040000
	s_addc_u32 s9, s49, 0
	v_writelane_b32 v251, s8, 1
	v_readlane_b32 s36, v248, 10
	v_readlane_b32 s50, v248, 24
	v_writelane_b32 v251, s9, 2
	s_add_u32 s8, s22, 0xf300000
	s_addc_u32 s9, s23, 0
	s_lshl_b32 s34, s19, 4
	v_writelane_b32 v251, s8, 3
	s_cmp_lt_i32 s21, s34
	v_readlane_b32 s51, v248, 25
	v_writelane_b32 v251, s9, 4
	s_cselect_b64 s[8:9], -1, 0
	v_writelane_b32 v251, s8, 5
	s_add_i32 s16, s24, s6
	s_add_i32 s20, s19, -8
	v_writelane_b32 v251, s9, 6
	s_lshr_b32 s8, s14, 29
	s_add_i32 s8, s21, s8
	v_writelane_b32 v251, s14, 7
	s_ashr_i32 s14, s8, 3
	s_and_b32 s8, s8, -8
	s_sub_i32 s15, s21, s8
	s_add_i32 s17, s16, -1
	s_add_i32 s8, s13, s10
	s_cmpk_lt_i32 s8, 0x3c80
	v_writelane_b32 v251, s8, 8
	s_cselect_b64 s[8:9], -1, 0
	v_writelane_b32 v251, s8, 9
	v_readlane_b32 s48, v248, 22
	v_readlane_b32 s49, v248, 23
	v_writelane_b32 v251, s9, 10
	s_add_u32 s8, s22, 0x85300000
	s_addc_u32 s9, s23, 0
	s_lshl_b32 s31, s19, 1
	v_writelane_b32 v251, s8, 11
	s_add_i32 s18, s10, s33
	s_or_b32 s33, s31, 1
	v_writelane_b32 v251, s9, 12
	s_add_u32 s8, s22, 0x76d00000
	v_writelane_b32 v251, s8, 13
	s_addc_u32 s8, s23, 0
	v_writelane_b32 v251, s8, 14
	s_add_u32 s8, s50, 0x4000
	s_addc_u32 s9, s51, 0
	v_writelane_b32 v251, s8, 15
	v_mov_b32_e32 v1, s15
	v_alignbit_b32 v1, s19, v1, 31
	v_writelane_b32 v251, s9, 16
	s_add_u32 s8, s48, 0x4000
	s_addc_u32 s9, s49, 0
	v_writelane_b32 v251, s8, 17
	v_readlane_b32 s37, v248, 11
	v_readlane_b32 s38, v248, 12
	v_writelane_b32 v251, s9, 18
	v_readlane_b32 s8, v248, 3
	v_readlane_b32 s9, v248, 4
	s_mov_b64 s[12:13], s[8:9]
	s_cmp_gt_i32 s12, 7
	v_readlane_b32 s10, v248, 5
	v_readlane_b32 s11, v248, 6
	s_cselect_b64 s[8:9], -1, 0
	s_cmp_lt_i32 s13, 9
	s_cselect_b64 s[10:11], -1, 0
	s_cmpk_lt_i32 s21, 0xc0
	s_cselect_b32 s7, s7, -1
	s_cmpk_gt_i32 s24, 0xc0
	s_cselect_b32 s7, s7, -2
	s_cmp_lg_u32 s7, 2
	s_cselect_b64 s[12:13], -1, 0
	v_writelane_b32 v251, s26, 19
	s_and_b64 s[12:13], s[26:27], s[12:13]
	s_cmp_lg_u32 s7, 1
	v_writelane_b32 v251, s27, 20
	v_writelane_b32 v251, s12, 21
	v_readlane_b32 s39, v248, 13
	v_readlane_b32 s40, v248, 14
	v_writelane_b32 v251, s13, 22
	v_writelane_b32 v251, s7, 23
	v_readfirstlane_b32 s7, v1
	v_writelane_b32 v251, s19, 24
	s_mul_i32 s7, s7, s15
	s_cselect_b64 s[12:13], -1, 0
	v_writelane_b32 v251, s12, 25
	s_add_i32 s7, s7, s14
	v_readlane_b32 s41, v248, 15
	v_writelane_b32 v251, s13, 26
	s_ashr_i32 s12, s7, 31
	s_lshr_b32 s12, s12, 25
	s_add_i32 s12, s7, s12
	s_ashr_i32 s12, s12, 7
	s_lshl_b32 s13, s12, 7
	s_sub_i32 s7, s7, s13
	s_lshl_b32 s12, s12, 3
	s_cmp_gt_i32 s12, s20
	s_cselect_b32 s13, 1, 8
	s_cmp_lt_i32 s15, 0
	s_cselect_b32 s19, s33, s31
	s_mul_i32 s15, s19, s15
	s_add_i32 s14, s15, s14
	v_cvt_f32_ubyte0_e32 v1, s13
	s_ashr_i32 s15, s14, 31
	v_rcp_iflag_f32_e32 v1, v1
	s_lshr_b32 s15, s15, 25
	s_add_i32 s15, s14, s15
	s_ashr_i32 s15, s15, 7
	s_lshl_b32 s19, s15, 7
	v_mul_f32_e32 v1, 0x4f7ffffe, v1
	v_writelane_b32 v251, s31, 27
	s_sub_i32 s14, s14, s19
	s_lshl_b32 s15, s15, 3
	v_cvt_u32_f32_e32 v1, v1
	v_writelane_b32 v251, s33, 28
	s_cmp_gt_i32 s15, s20
	v_writelane_b32 v251, s20, 29
	s_cselect_b32 s19, 1, 8
	s_or_b64 s[8:9], s[8:9], s[10:11]
	v_writelane_b32 v251, s8, 30
	s_mov_b32 s33, 0xbcf5c28f
	v_readlane_b32 s42, v248, 16
	v_writelane_b32 v251, s9, 31
	s_sub_i32 s8, 0, s13
	v_readfirstlane_b32 s9, v1
	s_mul_i32 s8, s8, s9
	s_mul_hi_u32 s8, s9, s8
	s_add_i32 s9, s9, s8
	s_abs_i32 s8, s7
	s_mul_hi_u32 s9, s8, s9
	s_mul_i32 s10, s9, s13
	s_sub_i32 s8, s8, s10
	s_ashr_i32 s10, s7, 31
	s_add_i32 s11, s9, 1
	s_sub_i32 s20, s8, s13
	s_cmp_ge_u32 s8, s13
	s_cselect_b32 s9, s11, s9
	s_cselect_b32 s8, s20, s8
	s_add_i32 s11, s9, 1
	s_cmp_ge_u32 s8, s13
	s_cselect_b32 s8, s11, s9
	s_xor_b32 s8, s8, s10
	s_sub_i32 s8, s8, s10
	v_writelane_b32 v251, s8, 32
	s_mul_i32 s8, s8, s13
	s_sub_i32 s7, s7, s8
	s_add_i32 s7, s12, s7
	v_writelane_b32 v251, s7, 33
	s_abs_i32 s7, s24
	v_cvt_f32_u32_e32 v1, s7
	s_sub_i32 s8, 0, s7
	v_readlane_b32 s43, v248, 17
	v_readlane_b32 s44, v248, 18
	v_rcp_iflag_f32_e32 v1, v1
	v_readlane_b32 s45, v248, 19
	v_readlane_b32 s46, v248, 20
	v_readlane_b32 s47, v248, 21
	v_mul_f32_e32 v1, 0x4f7ffffe, v1
	v_cvt_u32_f32_e32 v1, v1
	s_nop 0
	v_readfirstlane_b32 s9, v1
	s_mul_i32 s8, s8, s9
	s_mul_hi_u32 s8, s9, s8
	s_add_i32 s9, s9, s8
	s_sub_i32 s8, 1, s16
	s_max_i32 s8, s17, s8
	s_mul_hi_u32 s9, s8, s9
	s_mul_i32 s10, s9, s7
	s_sub_i32 s8, s8, s10
	s_xor_b32 s10, s17, s24
	s_ashr_i32 s10, s10, 31
	s_add_i32 s11, s9, 1
	s_sub_i32 s12, s8, s7
	s_cmp_ge_u32 s8, s7
	s_cselect_b32 s9, s11, s9
	s_cselect_b32 s8, s12, s8
	s_add_i32 s11, s9, 1
	s_cmp_ge_u32 s8, s7
	s_cselect_b32 s7, s11, s9
	s_xor_b32 s7, s7, s10
	s_not_b32 s8, s10
	s_add_i32 s7, s8, s7
	s_mul_i32 s7, s7, s24
	s_sub_i32 s6, s6, s7
	s_sub_i32 s7, s24, s6
	v_cvt_f32_ubyte0_e32 v1, s19
	s_cmp_lt_i32 s7, 1
	v_rcp_iflag_f32_e32 v1, v1
	s_cselect_b64 s[8:9], -1, 0
	v_writelane_b32 v251, s8, 34
	s_cmp_ge_i32 s21, s6
	v_mul_f32_e32 v1, 0x4f7ffffe, v1
	v_writelane_b32 v251, s9, 35
	s_cselect_b64 s[8:9], -1, 0
	s_sub_i32 s6, s21, s6
	v_writelane_b32 v251, s8, 36
	s_lshl_b32 s6, s6, 3
	s_add_i32 s6, s18, s6
	v_writelane_b32 v251, s9, 37
	s_lshl_b32 s7, s7, 3
	v_cvt_u32_f32_e32 v1, v1
	v_writelane_b32 v251, s7, 38
	s_cmpk_lt_i32 s6, 0x3c80
	v_writelane_b32 v251, s6, 39
	s_cselect_b64 s[6:7], -1, 0
	v_writelane_b32 v251, s6, 40
	s_nop 1
	v_writelane_b32 v251, s7, 41
	s_sub_i32 s6, 0, s19
	v_readfirstlane_b32 s7, v1
	s_mul_i32 s6, s6, s7
	s_mul_hi_u32 s6, s7, s6
	s_add_i32 s7, s7, s6
	s_abs_i32 s6, s14
	s_mul_hi_u32 s7, s6, s7
	s_mul_i32 s8, s7, s19
	s_sub_i32 s6, s6, s8
	s_ashr_i32 s8, s14, 31
	s_add_i32 s9, s7, 1
	s_sub_i32 s10, s6, s19
	s_cmp_ge_u32 s6, s19
	s_cselect_b32 s7, s9, s7
	s_cselect_b32 s6, s10, s6
	s_add_i32 s9, s7, 1
	s_cmp_ge_u32 s6, s19
	s_cselect_b32 s6, s9, s7
	s_xor_b32 s6, s6, s8
	s_sub_i32 s8, s6, s8
	s_mul_i32 s6, s8, s19
	s_sub_i32 s6, s14, s6
	s_add_i32 s10, s15, s6
	s_lshl_b32 s6, s21, 8
	v_writelane_b32 v251, s6, 42
	s_lshl_b32 s6, s24, 8
	v_writelane_b32 v251, s6, 43
	v_writelane_b32 v251, s25, 44
	s_lshl_b32 s6, s25, 8
	v_writelane_b32 v251, s6, 45
	s_mov_b32 s6, s10
	s_ashr_i32 s11, s10, 31
	v_writelane_b32 v251, s6, 46
	s_ashr_i32 s9, s8, 31
	v_mbcnt_lo_u32_b32 v1, -1, 0
	v_writelane_b32 v251, s7, 47
	s_lshl_b64 s[6:7], s[10:11], 21
	v_writelane_b32 v251, s6, 48
	v_mbcnt_hi_u32_b32 v229, -1, v1
	s_nop 0
	v_writelane_b32 v251, s7, 49
	s_mov_b32 s6, s8
	v_writelane_b32 v251, s6, 50
	s_nop 1
	v_writelane_b32 v251, s7, 51
	s_lshl_b64 s[6:7], s[8:9], 21
	s_add_u32 s4, s4, s28
	s_addc_u32 s5, s5, s29
	s_add_u32 s4, s22, s4
	v_writelane_b32 v251, s6, 52
	s_addc_u32 s5, s23, s5
	s_add_u32 s4, s4, 0x1e500100
	v_writelane_b32 v251, s7, 53
	v_writelane_b32 v251, s4, 54
	s_addc_u32 s4, s5, 0
	v_writelane_b32 v251, s4, 55
	s_add_u32 s4, s28, 0x55b80080
	v_writelane_b32 v251, s4, 56
	v_writelane_b32 v251, s28, 57
	s_addc_u32 s4, s29, 0
	s_or_b32 s0, s0, s30
	v_writelane_b32 v251, s29, 58
	s_mov_b32 s5, 0
	v_writelane_b32 v251, s4, 59
	s_add_u32 s0, s22, s0
	s_mov_b32 s35, s5
	s_addc_u32 s1, s23, s1
	v_writelane_b32 v251, s34, 60
	s_add_u32 s0, s0, 0x24500100
	s_mov_b64 s[6:7], -1
	v_writelane_b32 v251, s35, 61
	v_writelane_b32 v251, s0, 62
	s_addc_u32 s0, s1, 0
	v_writelane_b32 v251, s0, 63
	s_mul_hi_i32 s1, s66, 0x3000
	s_mul_i32 s0, s66, 0x3000
	v_writelane_b32 v252, s0, 0
	s_ashr_i32 s67, s66, 31
	s_mov_b32 s12, s5
	v_writelane_b32 v252, s1, 1
	s_lshl_b32 s0, s2, 1
	v_writelane_b32 v252, s0, 2
	s_lshl_b32 s0, s3, 2
	v_writelane_b32 v252, s0, 3
	v_writelane_b32 v252, s30, 4
	s_or_b32 s0, s30, 0x6a800080
	v_writelane_b32 v252, s0, 5
	s_add_i32 s0, 0, 0x19800
	v_writelane_b32 v252, s0, 6
	v_cmp_eq_u32_e64 s[0:1], 0, v0
	s_mov_b64 s[2:3], 0x80
	s_nop 0
	v_writelane_b32 v252, s0, 7
	s_nop 1
	v_writelane_b32 v252, s1, 8
	s_lshl_b64 s[0:1], s[66:67], 12
	v_writelane_b32 v252, s0, 9
	s_nop 1
	v_writelane_b32 v252, s1, 10
	s_lshl_b64 s[0:1], s[66:67], 7
	v_writelane_b32 v252, s0, 11
	s_nop 1
	v_writelane_b32 v252, s1, 12
	s_lshl_b64 s[0:1], s[66:67], 13
	v_writelane_b32 v252, s0, 13
	s_nop 1
	v_writelane_b32 v252, s1, 14
	s_mov_b32 s1, 0
	v_writelane_b32 v252, s0, 15
	s_nop 1
	v_writelane_b32 v252, s1, 16
	v_writelane_b32 v252, s66, 17
	s_nop 1
	v_writelane_b32 v252, s67, 18
	s_branch .LBB0_84

.LBB0_1497:
	s_or_b64 exec, exec, s[4:5]
	v_readfirstlane_b32 s4, v0
	s_lshl_b32 s4, s4, 8
	s_and_b32 s4, s4, 0x7fffc000
	s_add_i32 s4, s4, 0
	v_add_u32_e32 v1, s4, v134
	s_waitcnt vmcnt(0)
	v_cvt_pk_bf16_f32 v139, v6, v4
	v_cvt_pk_bf16_f32 v4, v11, v9
	v_cvt_pk_bf16_f32 v5, v7, v5
	v_cvt_pk_bf16_f32 v6, v25, v21
	v_cvt_pk_bf16_f32 v7, v17, v13
	ds_write_b128 v1, v[4:7] offset:128
	v_cvt_pk_bf16_f32 v4, v27, v23
	v_cvt_pk_bf16_f32 v5, v19, v15
	v_cvt_pk_bf16_f32 v6, v43, v39
	v_cvt_pk_bf16_f32 v7, v33, v29
	v_cvt_pk_bf16_f32 v138, v10, v8
	v_cvt_pk_bf16_f32 v140, v24, v20
	v_cvt_pk_bf16_f32 v141, v16, v12
	ds_write_b128 v1, v[4:7] offset:144
	v_cvt_pk_bf16_f32 v4, v45, v41
	v_cvt_pk_bf16_f32 v5, v37, v31
	v_cvt_pk_bf16_f32 v6, v59, v55
	v_cvt_pk_bf16_f32 v7, v51, v47
	ds_write_b128 v1, v[138:141]
	v_cvt_pk_bf16_f32 v138, v26, v22
	v_cvt_pk_bf16_f32 v139, v18, v14
	v_cvt_pk_bf16_f32 v140, v42, v38
	v_cvt_pk_bf16_f32 v141, v32, v28
	ds_write_b128 v1, v[4:7] offset:160
	v_cvt_pk_bf16_f32 v4, v61, v57
	v_cvt_pk_bf16_f32 v5, v53, v49
	v_cvt_pk_bf16_f32 v6, v75, v71
	v_cvt_pk_bf16_f32 v7, v67, v63
	ds_write_b128 v1, v[138:141] offset:16
	v_cvt_pk_bf16_f32 v138, v44, v40
	v_cvt_pk_bf16_f32 v139, v36, v30
	v_cvt_pk_bf16_f32 v140, v58, v54
	v_cvt_pk_bf16_f32 v141, v50, v46
	ds_write_b128 v1, v[4:7] offset:176
	v_cvt_pk_bf16_f32 v4, v77, v73
	v_cvt_pk_bf16_f32 v5, v69, v65
	v_cvt_pk_bf16_f32 v6, v91, v87
	v_cvt_pk_bf16_f32 v7, v83, v79
	ds_write_b128 v1, v[138:141] offset:32
	v_cvt_pk_bf16_f32 v138, v60, v56
	v_cvt_pk_bf16_f32 v139, v52, v48
	v_cvt_pk_bf16_f32 v140, v74, v70
	v_cvt_pk_bf16_f32 v141, v66, v62
	ds_write_b128 v1, v[4:7] offset:192
	v_cvt_pk_bf16_f32 v4, v93, v89
	v_cvt_pk_bf16_f32 v5, v85, v81
	v_cvt_pk_bf16_f32 v6, v107, v103
	v_cvt_pk_bf16_f32 v7, v99, v95
	ds_write_b128 v1, v[138:141] offset:48
	v_cvt_pk_bf16_f32 v138, v76, v72
	v_cvt_pk_bf16_f32 v139, v68, v64
	v_cvt_pk_bf16_f32 v140, v90, v86
	v_cvt_pk_bf16_f32 v141, v82, v78
	ds_write_b128 v1, v[4:7] offset:208
	v_cvt_pk_bf16_f32 v4, v109, v105
	v_cvt_pk_bf16_f32 v5, v101, v97
	v_cvt_pk_bf16_f32 v6, v123, v119
	v_cvt_pk_bf16_f32 v7, v115, v111
	ds_write_b128 v1, v[138:141] offset:64
	v_cvt_pk_bf16_f32 v138, v92, v88
	v_cvt_pk_bf16_f32 v139, v84, v80
	v_cvt_pk_bf16_f32 v140, v106, v102
	v_cvt_pk_bf16_f32 v141, v98, v94
	ds_write_b128 v1, v[4:7] offset:224
	v_cvt_pk_bf16_f32 v4, v125, v121
	v_cvt_pk_bf16_f32 v5, v117, v113
	v_cvt_pk_bf16_f32 v6, v133, v131
	v_cvt_pk_bf16_f32 v7, v129, v127
	ds_write_b128 v1, v[138:141] offset:80
	v_cvt_pk_bf16_f32 v138, v108, v104
	v_cvt_pk_bf16_f32 v139, v100, v96
	v_cvt_pk_bf16_f32 v140, v122, v118
	v_cvt_pk_bf16_f32 v141, v114, v110
	ds_write_b128 v1, v[4:7] offset:240
	v_add_u32_e32 v4, s8, v135
	ds_write_b128 v1, v[138:141] offset:96
	v_cvt_pk_bf16_f32 v138, v124, v120
	v_cvt_pk_bf16_f32 v139, v116, v112
	v_cvt_pk_bf16_f32 v140, v132, v130
	v_cvt_pk_bf16_f32 v141, v128, v126
	v_ashrrev_i32_e32 v5, 31, v4
	v_readlane_b32 s8, v251, 3
	ds_write_b128 v1, v[138:141] offset:112
	v_lshlrev_b64 v[4:5], 13, v[4:5]
	v_readlane_b32 s9, v251, 4
	v_add_u32_e32 v1, s4, v136
	v_mov_b32_e32 v3, v34
	v_lshl_add_u64 v[8:9], s[8:9], 0, v[4:5]
	ds_read_b128 v[4:7], v1
	v_lshl_add_u64 v[8:9], s[0:1], 1, v[8:9]
	v_lshl_add_u64 v[12:13], v[8:9], 0, v[2:3]
	ds_read_b128 v[8:11], v1 offset:1024
	s_mov_b32 s0, 0x10000
	s_waitcnt lgkmcnt(0)
	global_store_dwordx4 v[12:13], v[4:7], off
	s_add_i32 s6, s6, 0x10000
	s_nop 0
	v_add_co_u32_e32 v4, vcc, s0, v12
	s_mov_b32 s0, 0x20000
	s_nop 0
	v_addc_co_u32_e32 v5, vcc, 0, v13, vcc
	global_store_dwordx4 v[4:5], v[8:11], off
	ds_read_b128 v[4:7], v1 offset:2048
	ds_read_b128 v[8:11], v1 offset:3072
	v_add_co_u32_e32 v14, vcc, s0, v12
	s_mov_b32 s0, 0x30000
	s_nop 0
	v_addc_co_u32_e32 v15, vcc, 0, v13, vcc
	s_waitcnt lgkmcnt(1)
	global_store_dwordx4 v[14:15], v[4:7], off
	s_nop 1
	v_add_co_u32_e32 v4, vcc, s0, v12
	s_mov_b32 s0, 0x40000
	s_nop 0
	v_addc_co_u32_e32 v5, vcc, 0, v13, vcc
	s_waitcnt lgkmcnt(0)
	global_store_dwordx4 v[4:5], v[8:11], off
	ds_read_b128 v[4:7], v1 offset:4096
	ds_read_b128 v[8:11], v1 offset:5120
	v_add_co_u32_e32 v14, vcc, s0, v12
	s_mov_b32 s0, 0x50000
	s_nop 0
	v_addc_co_u32_e32 v15, vcc, 0, v13, vcc
	s_waitcnt lgkmcnt(1)
	global_store_dwordx4 v[14:15], v[4:7], off
	s_nop 1
	v_add_co_u32_e32 v4, vcc, s0, v12
	s_mov_b32 s0, 0x60000
	s_nop 0
	v_addc_co_u32_e32 v5, vcc, 0, v13, vcc
	s_waitcnt lgkmcnt(0)
	global_store_dwordx4 v[4:5], v[8:11], off
	ds_read_b128 v[4:7], v1 offset:6144
	ds_read_b128 v[8:11], v1 offset:7168
	v_add_co_u32_e32 v14, vcc, s0, v12
	s_mov_b32 s0, 0x70000
	s_nop 0
	v_addc_co_u32_e32 v15, vcc, 0, v13, vcc
	s_waitcnt lgkmcnt(1)
	global_store_dwordx4 v[14:15], v[4:7], off
	s_nop 1
	v_add_co_u32_e32 v4, vcc, s0, v12
	s_mov_b32 s0, 0x80000
	s_nop 0
	v_addc_co_u32_e32 v5, vcc, 0, v13, vcc
	s_waitcnt lgkmcnt(0)
	global_store_dwordx4 v[4:5], v[8:11], off
	ds_read_b128 v[4:7], v1 offset:8192
	ds_read_b128 v[8:11], v1 offset:9216
	v_add_co_u32_e32 v14, vcc, s0, v12
	s_mov_b32 s0, 0x90000
	s_nop 0
	v_addc_co_u32_e32 v15, vcc, 0, v13, vcc
	s_waitcnt lgkmcnt(1)
	global_store_dwordx4 v[14:15], v[4:7], off
	s_nop 1
	v_add_co_u32_e32 v4, vcc, s0, v12
	s_mov_b32 s0, 0xa0000
	s_nop 0
	v_addc_co_u32_e32 v5, vcc, 0, v13, vcc
	s_waitcnt lgkmcnt(0)
	global_store_dwordx4 v[4:5], v[8:11], off
	ds_read_b128 v[4:7], v1 offset:10240
	ds_read_b128 v[8:11], v1 offset:11264
	v_add_co_u32_e32 v14, vcc, s0, v12
	s_mov_b32 s0, 0xb0000
	s_nop 0
	v_addc_co_u32_e32 v15, vcc, 0, v13, vcc
	s_waitcnt lgkmcnt(1)
	global_store_dwordx4 v[14:15], v[4:7], off
	s_nop 1
	v_add_co_u32_e32 v4, vcc, s0, v12
	s_mov_b32 s0, 0xc0000
	s_nop 0
	v_addc_co_u32_e32 v5, vcc, 0, v13, vcc
	s_waitcnt lgkmcnt(0)
	global_store_dwordx4 v[4:5], v[8:11], off
	ds_read_b128 v[4:7], v1 offset:12288
	ds_read_b128 v[8:11], v1 offset:13312
	v_add_co_u32_e32 v14, vcc, s0, v12
	s_mov_b32 s0, 0xd0000
	s_nop 0
	v_addc_co_u32_e32 v15, vcc, 0, v13, vcc
	s_waitcnt lgkmcnt(1)
	global_store_dwordx4 v[14:15], v[4:7], off
	s_nop 1
	v_add_co_u32_e32 v4, vcc, s0, v12
	s_add_i32 s0, s7, 0x200
	s_nop 0
	v_addc_co_u32_e32 v5, vcc, 0, v13, vcc
	s_waitcnt lgkmcnt(0)
	global_store_dwordx4 v[4:5], v[8:11], off
	ds_read_b128 v[4:7], v1 offset:14336
	ds_read_b128 v[8:11], v1 offset:15360
	v_add_co_u32_e32 v14, vcc, 0xe0000, v12
	s_cmpk_lt_i32 s7, 0x280
	s_nop 0
	v_addc_co_u32_e32 v15, vcc, 0, v13, vcc
	s_waitcnt lgkmcnt(1)
	global_store_dwordx4 v[14:15], v[4:7], off
	s_mov_b32 s7, s0
	s_nop 0
	v_add_co_u32_e32 v4, vcc, 0xf0000, v12
	s_nop 1
	v_addc_co_u32_e32 v5, vcc, 0, v13, vcc
	s_waitcnt lgkmcnt(0)
	global_store_dwordx4 v[4:5], v[8:11], off
	s_cbranch_scc0 .LBB0_1506
